# restore explicit lgkmcnt waits covering V-fragment ds_reads before PV MFMAs (placed at first use)
# speedup vs baseline: 1.0557x; 1.0039x over previous
.LBB0_52:
	v_mul_f32_e32 v195, 0xbe38aa3b, v199
	v_fmamk_f32 v167, v167, 0x3e38aa3b, v195
	v_exp_f32_e32 v194, v167
	v_fmamk_f32 v167, v168, 0x3e38aa3b, v195
	v_fmamk_f32 v163, v163, 0x3e38aa3b, v195
	v_fmamk_f32 v159, v159, 0x3e38aa3b, v195
	v_mul_f32_e32 v196, 0xbe38aa3b, v201
	v_fmamk_f32 v166, v166, 0x3e38aa3b, v195
	v_exp_f32_e32 v168, v167
	v_fmamk_f32 v167, v169, 0x3e38aa3b, v195
	v_exp_f32_e32 v204, v163
	v_fmamk_f32 v163, v164, 0x3e38aa3b, v195
	v_exp_f32_e32 v208, v159
	v_fmamk_f32 v159, v160, 0x3e38aa3b, v195
	v_fmamk_f32 v155, v155, 0x3e38aa3b, v195
	v_fmamk_f32 v150, v150, 0x3e38aa3b, v196
	v_exp_f32_e32 v166, v166
	v_exp_f32_e32 v202, v167
	v_fmamk_f32 v162, v162, 0x3e38aa3b, v195
	v_exp_f32_e32 v164, v163
	v_fmamk_f32 v163, v165, 0x3e38aa3b, v195
	v_fmamk_f32 v158, v158, 0x3e38aa3b, v195
	v_exp_f32_e32 v160, v159
	v_fmamk_f32 v159, v161, 0x3e38aa3b, v195
	v_fmamk_f32 v154, v154, 0x3e38aa3b, v195
	v_exp_f32_e32 v212, v155
	v_fmamk_f32 v155, v156, 0x3e38aa3b, v195
	v_fmac_f32_e32 v195, 0x3e38aa3b, v157
	v_exp_f32_e32 v167, v150
	v_fmamk_f32 v150, v151, 0x3e38aa3b, v196
	v_exp_f32_e32 v216, v195
	v_exp_f32_e32 v195, v150
	v_fmamk_f32 v150, v152, 0x3e38aa3b, v196
	v_exp_f32_e32 v169, v150
	v_fmamk_f32 v150, v153, 0x3e38aa3b, v196
	v_exp_f32_e32 v203, v150
	v_fmamk_f32 v146, v146, 0x3e38aa3b, v196
	v_exp_f32_e32 v162, v162
	v_exp_f32_e32 v206, v163
	v_exp_f32_e32 v163, v146
	v_fmamk_f32 v146, v147, 0x3e38aa3b, v196
	v_pk_add_f32 v[150:151], v[166:167], 0 op_sel_hi:[1,0]
	v_exp_f32_e32 v205, v146
	v_fmamk_f32 v146, v148, 0x3e38aa3b, v196
	v_pk_add_f32 v[150:151], v[194:195], v[150:151]
	v_exp_f32_e32 v165, v146
	v_fmamk_f32 v146, v149, 0x3e38aa3b, v196
	v_pk_add_f32 v[150:151], v[168:169], v[150:151]
	v_exp_f32_e32 v207, v146
	v_pk_add_f32 v[150:151], v[202:203], v[150:151]
	v_fmamk_f32 v142, v142, 0x3e38aa3b, v196
	v_exp_f32_e32 v158, v158
	v_exp_f32_e32 v210, v159
	v_pk_add_f32 v[150:151], v[162:163], v[150:151]
	v_exp_f32_e32 v159, v142
	v_fmamk_f32 v142, v143, 0x3e38aa3b, v196
	v_pk_add_f32 v[150:151], v[204:205], v[150:151]
	v_exp_f32_e32 v209, v142
	v_fmamk_f32 v142, v144, 0x3e38aa3b, v196
	v_fmamk_f32 v138, v138, 0x3e38aa3b, v196
	v_exp_f32_e32 v156, v155
	v_pk_add_f32 v[150:151], v[164:165], v[150:151]
	v_exp_f32_e32 v161, v142
	v_fmamk_f32 v142, v145, 0x3e38aa3b, v196
	v_exp_f32_e32 v155, v138
	v_fmamk_f32 v138, v139, 0x3e38aa3b, v196
	v_pk_add_f32 v[150:151], v[206:207], v[150:151]
	v_exp_f32_e32 v211, v142
	v_exp_f32_e32 v213, v138
	v_fmamk_f32 v138, v140, 0x3e38aa3b, v196
	v_exp_f32_e32 v154, v154
	v_exp_f32_e32 v157, v138
	v_pk_add_f32 v[138:139], v[158:159], v[150:151]
	v_fmac_f32_e32 v196, 0x3e38aa3b, v141
	v_pk_add_f32 v[138:139], v[208:209], v[138:139]
	v_exp_f32_e32 v217, v196
	v_pk_add_f32 v[138:139], v[160:161], v[138:139]
	v_cvt_pk_bf16_f32 v146, v166, v194
	v_pk_add_f32 v[138:139], v[210:211], v[138:139]
	v_cvt_pk_bf16_f32 v147, v168, v202
	v_pk_add_f32 v[138:139], v[154:155], v[138:139]
	v_cvt_pk_bf16_f32 v148, v162, v204
	v_pk_add_f32 v[138:139], v[212:213], v[138:139]
	v_cvt_pk_bf16_f32 v149, v164, v206
	v_pk_add_f32 v[138:139], v[156:157], v[138:139]
	v_cvt_pk_bf16_f32 v140, v154, v212
	v_pk_add_f32 v[142:143], v[216:217], v[138:139]
	v_cvt_pk_bf16_f32 v138, v158, v208
	v_cvt_pk_bf16_f32 v139, v160, v210
	v_cvt_pk_bf16_f32 v141, v156, v216
	v_pk_add_f32 v[178:179], v[142:143], v[178:179]
	v_cvt_pk_bf16_f32 v142, v167, v195
	v_cvt_pk_bf16_f32 v143, v169, v203
	v_cvt_pk_bf16_f32 v144, v163, v205
	v_cvt_pk_bf16_f32 v145, v165, v207
	v_cvt_pk_bf16_f32 v150, v159, v209
	v_cvt_pk_bf16_f32 v151, v161, v211
	v_cvt_pk_bf16_f32 v152, v155, v213
	v_cvt_pk_bf16_f32 v153, v157, v217
	ds_read_b128 v[154:157], v0 offset:16384
	ds_read_b128 v[158:161], v0 offset:17408
	ds_read_b128 v[162:165], v0 offset:18432
	ds_read_b128 v[166:169], v0 offset:19456
	ds_read_b128 v[202:205], v0 offset:20480
	ds_read_b128 v[206:209], v0 offset:21504
	ds_read_b128 v[210:213], v0 offset:22528
	ds_read_b128 v[216:219], v0 offset:23552
	s_waitcnt lgkmcnt(8)
	v_mfma_f32_16x16x32_bf16 v[90:93], v[134:137], v[146:149], v[90:93]
	v_mfma_f32_16x16x32_bf16 v[70:73], v[134:137], v[142:145], v[70:73]
	v_mfma_f32_16x16x32_bf16 v[102:105], v[126:129], v[146:149], v[102:105]
	v_mfma_f32_16x16x32_bf16 v[66:69], v[126:129], v[142:145], v[66:69]
	v_mfma_f32_16x16x32_bf16 v[98:101], v[118:121], v[146:149], v[98:101]
	v_mfma_f32_16x16x32_bf16 v[58:61], v[118:121], v[142:145], v[58:61]
	v_mfma_f32_16x16x32_bf16 v[94:97], v[110:113], v[146:149], v[94:97]
	v_mfma_f32_16x16x32_bf16 v[54:57], v[110:113], v[142:145], v[54:57]
	s_waitcnt lgkmcnt(7)
	v_mfma_f32_16x16x32_bf16 v[86:89], v[154:157], v[146:149], v[86:89]
	v_mfma_f32_16x16x32_bf16 v[46:49], v[154:157], v[142:145], v[46:49]
	s_waitcnt lgkmcnt(5)
	v_mfma_f32_16x16x32_bf16 v[82:85], v[162:165], v[146:149], v[82:85]
	v_mfma_f32_16x16x32_bf16 v[38:41], v[162:165], v[142:145], v[38:41]
	s_waitcnt lgkmcnt(3)
	v_mfma_f32_16x16x32_bf16 v[78:81], v[202:205], v[146:149], v[78:81]
	v_mfma_f32_16x16x32_bf16 v[34:37], v[202:205], v[142:145], v[34:37]
	s_waitcnt lgkmcnt(1)
	v_mfma_f32_16x16x32_bf16 v[74:77], v[210:213], v[146:149], v[74:77]
	v_mfma_f32_16x16x32_bf16 v[26:29], v[210:213], v[142:145], v[26:29]
	v_mfma_f32_16x16x32_bf16 v[90:93], v[130:133], v[138:141], v[90:93]
	v_mfma_f32_16x16x32_bf16 v[70:73], v[130:133], v[150:153], v[70:73]
	v_mfma_f32_16x16x32_bf16 v[102:105], v[122:125], v[138:141], v[102:105]
	v_mfma_f32_16x16x32_bf16 v[66:69], v[122:125], v[150:153], v[66:69]
	v_mfma_f32_16x16x32_bf16 v[98:101], v[114:117], v[138:141], v[98:101]
	v_mfma_f32_16x16x32_bf16 v[58:61], v[114:117], v[150:153], v[58:61]
	v_mfma_f32_16x16x32_bf16 v[94:97], v[106:109], v[138:141], v[94:97]
	v_mfma_f32_16x16x32_bf16 v[54:57], v[106:109], v[150:153], v[54:57]
	v_mfma_f32_16x16x32_bf16 v[86:89], v[158:161], v[138:141], v[86:89]
	v_mfma_f32_16x16x32_bf16 v[46:49], v[158:161], v[150:153], v[46:49]
	v_mfma_f32_16x16x32_bf16 v[82:85], v[166:169], v[138:141], v[82:85]
	v_mfma_f32_16x16x32_bf16 v[38:41], v[166:169], v[150:153], v[38:41]
	v_mfma_f32_16x16x32_bf16 v[78:81], v[206:209], v[138:141], v[78:81]
	v_mfma_f32_16x16x32_bf16 v[34:37], v[206:209], v[150:153], v[34:37]
	s_waitcnt lgkmcnt(0)
	v_mfma_f32_16x16x32_bf16 v[74:77], v[216:219], v[138:141], v[74:77]
	v_mfma_f32_16x16x32_bf16 v[26:29], v[216:219], v[150:153], v[26:29]
	s_xor_b32 s53, s53, 1
	s_add_i32 s49, s49, 64
	s_add_i32 s54, s54, 1
	s_add_u32 s98, s98, 0x4000
	s_addc_u32 s99, s99, 0
	s_add_u32 s2, s2, 0x2000
	s_addc_u32 s3, s3, 0
	s_cmp_lg_u32 s1, s54
	s_cbranch_scc0 .LBB0_42
	v_mov_b32_e32 v200, v199
	v_mov_b32_e32 v198, v201
	s_branch .LBB0_46

.LBB0_407:
	v_mul_f32_e32 v170, 0xbe38aa3b, v169
	v_cndmask_b32_e64 v170, v222, v170, s[40:41]
	v_fmamk_f32 v18, v18, 0x3e38aa3b, v170
	v_fmamk_f32 v2, v2, 0x3e38aa3b, v170
	v_exp_f32_e32 v18, v18
	v_exp_f32_e32 v2, v2
	v_fmamk_f32 v19, v19, 0x3e38aa3b, v170
	v_fmamk_f32 v3, v3, 0x3e38aa3b, v170
	v_exp_f32_e32 v19, v19
	v_exp_f32_e32 v3, v3
	v_add_f32_e32 v177, v18, v2
	v_fmamk_f32 v20, v20, 0x3e38aa3b, v170
	v_fmamk_f32 v4, v4, 0x3e38aa3b, v170
	v_exp_f32_e32 v20, v20
	v_exp_f32_e32 v4, v4
	v_add_f32_e32 v176, v19, v3
	v_add_f32_e32 v177, v176, v177
	v_fmamk_f32 v21, v21, 0x3e38aa3b, v170
	v_fmamk_f32 v5, v5, 0x3e38aa3b, v170
	v_exp_f32_e32 v21, v21
	v_exp_f32_e32 v5, v5
	v_add_f32_e32 v176, v20, v4
	v_add_f32_e32 v177, v176, v177
	v_fmamk_f32 v22, v22, 0x3e38aa3b, v170
	v_fmamk_f32 v6, v6, 0x3e38aa3b, v170
	v_exp_f32_e32 v22, v22
	v_exp_f32_e32 v6, v6
	v_add_f32_e32 v176, v21, v5
	v_add_f32_e32 v177, v176, v177
	v_fmamk_f32 v23, v23, 0x3e38aa3b, v170
	v_fmamk_f32 v7, v7, 0x3e38aa3b, v170
	v_exp_f32_e32 v23, v23
	v_exp_f32_e32 v7, v7
	v_add_f32_e32 v176, v22, v6
	v_add_f32_e32 v177, v176, v177
	v_fmamk_f32 v24, v24, 0x3e38aa3b, v170
	v_fmamk_f32 v8, v8, 0x3e38aa3b, v170
	v_exp_f32_e32 v24, v24
	v_exp_f32_e32 v8, v8
	v_add_f32_e32 v176, v23, v7
	v_add_f32_e32 v177, v176, v177
	v_fmamk_f32 v25, v25, 0x3e38aa3b, v170
	v_fmamk_f32 v9, v9, 0x3e38aa3b, v170
	v_exp_f32_e32 v25, v25
	v_exp_f32_e32 v9, v9
	v_add_f32_e32 v176, v24, v8
	v_add_f32_e32 v177, v176, v177
	v_fmamk_f32 v26, v26, 0x3e38aa3b, v170
	v_fmamk_f32 v10, v10, 0x3e38aa3b, v170
	v_exp_f32_e32 v26, v26
	v_exp_f32_e32 v10, v10
	v_add_f32_e32 v176, v25, v9
	v_add_f32_e32 v177, v176, v177
	v_fmamk_f32 v27, v27, 0x3e38aa3b, v170
	v_fmamk_f32 v11, v11, 0x3e38aa3b, v170
	v_exp_f32_e32 v27, v27
	v_exp_f32_e32 v11, v11
	v_add_f32_e32 v176, v26, v10
	v_add_f32_e32 v177, v176, v177
	v_fmamk_f32 v28, v28, 0x3e38aa3b, v170
	v_fmamk_f32 v12, v12, 0x3e38aa3b, v170
	v_exp_f32_e32 v28, v28
	v_exp_f32_e32 v12, v12
	v_add_f32_e32 v176, v27, v11
	v_add_f32_e32 v177, v176, v177
	v_fmamk_f32 v29, v29, 0x3e38aa3b, v170
	v_fmamk_f32 v13, v13, 0x3e38aa3b, v170
	v_exp_f32_e32 v29, v29
	v_exp_f32_e32 v13, v13
	v_add_f32_e32 v176, v28, v12
	v_add_f32_e32 v177, v176, v177
	v_fmamk_f32 v30, v30, 0x3e38aa3b, v170
	v_fmamk_f32 v14, v14, 0x3e38aa3b, v170
	v_exp_f32_e32 v30, v30
	v_exp_f32_e32 v14, v14
	v_add_f32_e32 v176, v29, v13
	v_add_f32_e32 v177, v176, v177
	v_fmamk_f32 v31, v31, 0x3e38aa3b, v170
	v_fmamk_f32 v15, v15, 0x3e38aa3b, v170
	v_exp_f32_e32 v31, v31
	v_exp_f32_e32 v15, v15
	v_add_f32_e32 v176, v30, v14
	v_add_f32_e32 v177, v176, v177
	v_fmamk_f32 v32, v32, 0x3e38aa3b, v170
	v_fmamk_f32 v16, v16, 0x3e38aa3b, v170
	v_exp_f32_e32 v32, v32
	v_exp_f32_e32 v16, v16
	v_add_f32_e32 v176, v31, v15
	v_add_f32_e32 v177, v176, v177
	v_fmamk_f32 v33, v33, 0x3e38aa3b, v170
	v_fmamk_f32 v17, v17, 0x3e38aa3b, v170
	v_exp_f32_e32 v33, v33
	v_exp_f32_e32 v17, v17
	v_add_f32_e32 v176, v32, v16
	v_add_f32_e32 v177, v176, v177
	v_add_f32_e32 v176, v33, v17
	v_add_f32_e32 v177, v176, v177
	v_cvt_pk_bf16_f32 v172, v18, v19
	v_cvt_pk_bf16_f32 v173, v20, v21
	v_cvt_pk_bf16_f32 v174, v22, v23
	v_cvt_pk_bf16_f32 v175, v24, v25
	v_cvt_pk_bf16_f32 v9, v8, v9
	v_cvt_pk_bf16_f32 v8, v6, v7
	s_waitcnt lgkmcnt(0)
	v_mfma_f32_32x32x16_bf16 v[82:97], v[158:161], v[172:175], v[82:97]
	v_cvt_pk_bf16_f32 v7, v4, v5
	v_cvt_pk_bf16_f32 v6, v2, v3
	v_mfma_f32_32x32x16_bf16 v[66:81], v[126:129], v[172:175], v[66:81]
	v_cvt_pk_bf16_f32 v2, v10, v11
	v_cvt_pk_bf16_f32 v3, v12, v13
	v_cvt_pk_bf16_f32 v4, v14, v15
	v_cvt_pk_bf16_f32 v5, v16, v17
	v_cvt_pk_bf16_f32 v10, v26, v27
	v_cvt_pk_bf16_f32 v11, v28, v29
	v_cvt_pk_bf16_f32 v12, v30, v31
	v_cvt_pk_bf16_f32 v13, v32, v33
	v_add_f32_e32 v201, v177, v201
	s_nop 0
	v_mfma_f32_32x32x16_bf16 v[82:97], v[154:157], v[10:13], v[82:97]
	v_mfma_f32_32x32x16_bf16 v[66:81], v[122:125], v[10:13], v[66:81]
	v_mfma_f32_32x32x16_bf16 v[82:97], v[150:153], v[6:9], v[82:97]
	v_mfma_f32_32x32x16_bf16 v[66:81], v[118:121], v[6:9], v[66:81]
	v_mfma_f32_32x32x16_bf16 v[82:97], v[146:149], v[2:5], v[82:97]
	v_mfma_f32_32x32x16_bf16 v[66:81], v[114:117], v[2:5], v[66:81]
	s_xor_b32 s49, s49, 1
	s_cmp_le_i32 s1, s80
	s_cbranch_scc1 .LBB0_409
	s_branch .LBB0_410

.LBB0_418:
	v_mul_f32_e32 v194, 0xbe38aa3b, v0
	s_add_i32 s94, s94, 1
	v_fmamk_f32 v114, v114, 0x3e38aa3b, v194
	v_fmamk_f32 v98, v98, 0x3e38aa3b, v194
	v_exp_f32_e32 v114, v114
	v_exp_f32_e32 v98, v98
	v_fmamk_f32 v115, v115, 0x3e38aa3b, v194
	v_fmamk_f32 v99, v99, 0x3e38aa3b, v194
	v_exp_f32_e32 v115, v115
	v_exp_f32_e32 v99, v99
	v_add_f32_e32 v196, v114, v98
	v_fmamk_f32 v116, v116, 0x3e38aa3b, v194
	v_fmamk_f32 v100, v100, 0x3e38aa3b, v194
	v_exp_f32_e32 v116, v116
	v_exp_f32_e32 v100, v100
	v_add_f32_e32 v195, v115, v99
	v_add_f32_e32 v196, v195, v196
	v_fmamk_f32 v117, v117, 0x3e38aa3b, v194
	v_fmamk_f32 v101, v101, 0x3e38aa3b, v194
	v_exp_f32_e32 v117, v117
	v_exp_f32_e32 v101, v101
	v_add_f32_e32 v195, v116, v100
	v_add_f32_e32 v196, v195, v196
	v_fmamk_f32 v118, v118, 0x3e38aa3b, v194
	v_fmamk_f32 v102, v102, 0x3e38aa3b, v194
	v_exp_f32_e32 v118, v118
	v_exp_f32_e32 v102, v102
	v_add_f32_e32 v195, v117, v101
	v_add_f32_e32 v196, v195, v196
	v_fmamk_f32 v119, v119, 0x3e38aa3b, v194
	v_fmamk_f32 v103, v103, 0x3e38aa3b, v194
	v_exp_f32_e32 v119, v119
	v_exp_f32_e32 v103, v103
	v_add_f32_e32 v195, v118, v102
	v_add_f32_e32 v196, v195, v196
	v_fmamk_f32 v120, v120, 0x3e38aa3b, v194
	v_fmamk_f32 v104, v104, 0x3e38aa3b, v194
	v_exp_f32_e32 v120, v120
	v_exp_f32_e32 v104, v104
	v_add_f32_e32 v195, v119, v103
	v_add_f32_e32 v196, v195, v196
	v_fmamk_f32 v121, v121, 0x3e38aa3b, v194
	v_fmamk_f32 v105, v105, 0x3e38aa3b, v194
	v_exp_f32_e32 v121, v121
	v_exp_f32_e32 v105, v105
	v_add_f32_e32 v195, v120, v104
	v_add_f32_e32 v196, v195, v196
	v_fmamk_f32 v122, v122, 0x3e38aa3b, v194
	v_fmamk_f32 v106, v106, 0x3e38aa3b, v194
	v_exp_f32_e32 v122, v122
	v_exp_f32_e32 v106, v106
	v_add_f32_e32 v195, v121, v105
	v_add_f32_e32 v196, v195, v196
	v_fmamk_f32 v123, v123, 0x3e38aa3b, v194
	v_fmamk_f32 v107, v107, 0x3e38aa3b, v194
	v_exp_f32_e32 v123, v123
	v_exp_f32_e32 v107, v107
	v_add_f32_e32 v195, v122, v106
	v_add_f32_e32 v196, v195, v196
	v_fmamk_f32 v124, v124, 0x3e38aa3b, v194
	v_fmamk_f32 v108, v108, 0x3e38aa3b, v194
	v_exp_f32_e32 v124, v124
	v_exp_f32_e32 v108, v108
	v_add_f32_e32 v195, v123, v107
	v_add_f32_e32 v196, v195, v196
	v_fmamk_f32 v125, v125, 0x3e38aa3b, v194
	v_fmamk_f32 v109, v109, 0x3e38aa3b, v194
	v_exp_f32_e32 v125, v125
	v_exp_f32_e32 v109, v109
	v_add_f32_e32 v195, v124, v108
	v_add_f32_e32 v196, v195, v196
	v_fmamk_f32 v126, v126, 0x3e38aa3b, v194
	v_fmamk_f32 v110, v110, 0x3e38aa3b, v194
	v_exp_f32_e32 v126, v126
	v_exp_f32_e32 v110, v110
	v_add_f32_e32 v195, v125, v109
	v_add_f32_e32 v196, v195, v196
	v_fmamk_f32 v127, v127, 0x3e38aa3b, v194
	v_fmamk_f32 v111, v111, 0x3e38aa3b, v194
	v_exp_f32_e32 v127, v127
	v_exp_f32_e32 v111, v111
	v_add_f32_e32 v195, v126, v110
	v_add_f32_e32 v196, v195, v196
	v_fmamk_f32 v128, v128, 0x3e38aa3b, v194
	v_fmamk_f32 v112, v112, 0x3e38aa3b, v194
	v_exp_f32_e32 v128, v128
	v_exp_f32_e32 v112, v112
	v_add_f32_e32 v195, v127, v111
	v_add_f32_e32 v196, v195, v196
	v_fmamk_f32 v129, v129, 0x3e38aa3b, v194
	v_fmamk_f32 v113, v113, 0x3e38aa3b, v194
	v_exp_f32_e32 v129, v129
	v_exp_f32_e32 v113, v113
	v_add_f32_e32 v195, v128, v112
	v_add_f32_e32 v196, v195, v196
	v_add_f32_e32 v195, v129, v113
	v_add_f32_e32 v196, v195, v196
	v_cvt_pk_bf16_f32 v208, v114, v115
	v_cvt_pk_bf16_f32 v209, v116, v117
	v_cvt_pk_bf16_f32 v210, v118, v119
	v_cvt_pk_bf16_f32 v211, v120, v121
	v_cvt_pk_bf16_f32 v105, v104, v105
	v_cvt_pk_bf16_f32 v104, v102, v103
	s_waitcnt lgkmcnt(0)
	v_mfma_f32_32x32x16_bf16 v[2:17], v[190:193], v[208:211], v[2:17]
	v_cvt_pk_bf16_f32 v103, v100, v101
	v_cvt_pk_bf16_f32 v102, v98, v99
	v_mfma_f32_32x32x16_bf16 v[18:33], v[174:177], v[208:211], v[18:33]
	v_cvt_pk_bf16_f32 v98, v106, v107
	v_cvt_pk_bf16_f32 v99, v108, v109
	v_cvt_pk_bf16_f32 v100, v110, v111
	v_cvt_pk_bf16_f32 v101, v112, v113
	v_cvt_pk_bf16_f32 v106, v122, v123
	v_cvt_pk_bf16_f32 v107, v124, v125
	v_cvt_pk_bf16_f32 v108, v126, v127
	v_cvt_pk_bf16_f32 v109, v128, v129
	v_add_f32_e32 v203, v196, v203
	s_nop 0
	v_mfma_f32_32x32x16_bf16 v[2:17], v[186:189], v[106:109], v[2:17]
	v_mfma_f32_32x32x16_bf16 v[18:33], v[170:173], v[106:109], v[18:33]
	v_mfma_f32_32x32x16_bf16 v[2:17], v[182:185], v[102:105], v[2:17]
	v_mfma_f32_32x32x16_bf16 v[18:33], v[166:169], v[102:105], v[18:33]
	v_mfma_f32_32x32x16_bf16 v[2:17], v[178:181], v[98:101], v[2:17]
	v_mfma_f32_32x32x16_bf16 v[18:33], v[162:165], v[98:101], v[18:33]
	s_xor_b32 s14, s14, 1
	s_add_i32 s13, s13, 64
	s_add_u32 s0, s0, 0x2000
	s_addc_u32 s1, s1, 0
	s_andn2_b64 vcc, exec, s[44:45]
	s_cbranch_vccz .LBB0_235
	v_mov_b32_e32 v242, v0
	s_branch .LBB0_412
